# norm1 phase: half of the workgroups run the norm first and the bias matvec second so latency-bound and bandwidth-bound work overlap across CUs
# baseline (speedup 1.0000x reference)
.LBB0_128:
	v_writelane_b32 v254, s88, 19
	s_cmp_lt_i32 s84, 2
	s_cselect_b64 s[2:3], -1, 0
	v_writelane_b32 v254, s89, 20
	v_writelane_b32 v254, s90, 21
	v_writelane_b32 v254, s91, 22
	v_writelane_b32 v254, s92, 23
	v_writelane_b32 v254, s93, 24
	v_writelane_b32 v254, s94, 25
	v_writelane_b32 v254, s95, 26
	s_add_u32 s90, s82, 0x3000000
	s_addc_u32 s91, s83, 0
	s_and_b64 s[4:5], s[2:3], s[6:7]
	s_andn2_b64 vcc, exec, s[4:5]
	s_mov_b64 s[88:89], s[72:73]
	s_mov_b32 s99, 0
	s_cbranch_vccnz .LBB0_153
	v_mov_b32_e32 v0, v236
	s_lshl_b32 s6, s96, 3
	v_readfirstlane_b32 s2, v0
	s_ashr_i32 s3, s2, 6
	s_lshl_b32 s8, s86, 3
	s_add_i32 s2, s3, s6
	s_cmpk_gt_i32 s2, 0x15ff
	v_and_b32_e32 v18, 63, v0
	s_cbranch_scc1 .LBB0_148
	s_bitcmp1_b32 s96, 3
	s_cbranch_scc0 .Lp1_sb
	s_mov_b32 s99, 1
	s_branch .LBB0_148
.Lp1_sb:
	v_mbcnt_lo_u32_b32 v0, -1, 0
	v_mbcnt_hi_u32_b32 v0, -1, v0
	v_and_b32_e32 v1, 64, v0
	v_add_u32_e32 v1, 64, v1
	v_xor_b32_e32 v2, 1, v0
	v_cmp_lt_i32_e32 vcc, v2, v1
	s_mov_b64 s[10:11], 0x16000
	s_ashr_i32 s7, s3, 31
	v_cndmask_b32_e32 v2, v0, v2, vcc
	v_lshlrev_b32_e32 v19, 2, v2
	v_xor_b32_e32 v2, 2, v0
	v_cmp_lt_i32_e32 vcc, v2, v1
	s_ashr_i32 s9, s6, 31
	s_add_u32 s12, s3, s6
	v_cndmask_b32_e32 v2, v0, v2, vcc
	v_lshlrev_b32_e32 v20, 2, v2
	v_xor_b32_e32 v2, 4, v0
	v_cmp_lt_i32_e32 vcc, v2, v1
	s_addc_u32 s13, s7, s9
	s_lshl_b64 s[6:7], s[12:13], 2
	v_cndmask_b32_e32 v2, v0, v2, vcc
	v_lshlrev_b32_e32 v21, 2, v2
	v_xor_b32_e32 v2, 8, v0
	v_cmp_lt_i32_e32 vcc, v2, v1
	s_lshl_b64 s[12:13], s[12:13], 11
	s_ashr_i32 s9, s8, 31
	v_cndmask_b32_e32 v2, v0, v2, vcc
	v_lshlrev_b32_e32 v22, 2, v2
	v_xor_b32_e32 v2, 16, v0
	v_cmp_lt_i32_e32 vcc, v2, v1
	v_lshl_or_b32 v16, v18, 3, s12
	v_mov_b32_e32 v17, s13
	v_cndmask_b32_e32 v2, v0, v2, vcc
	v_lshlrev_b32_e32 v23, 2, v2
	v_xor_b32_e32 v2, 32, v0
	v_cmp_lt_i32_e32 vcc, v2, v1
	v_mov_b32_e32 v1, 0
	s_mov_b64 s[12:13], 0x1300400
	v_cndmask_b32_e32 v0, v0, v2, vcc
	v_lshlrev_b32_e32 v24, 2, v0
	v_lshlrev_b32_e32 v0, 4, v18
	v_lshl_add_u64 v[14:15], s[82:83], 0, v[0:1]
	v_lshl_add_u64 v[0:1], v[14:15], 0, s[10:11]
	s_mov_b64 s[10:11], 0x1f000
	v_lshl_add_u64 v[2:3], v[14:15], 0, s[10:11]
	s_mov_b64 s[10:11], 0x28000
	v_lshl_add_u64 v[4:5], v[14:15], 0, s[10:11]
	s_mov_b64 s[10:11], 0x31000
	v_lshl_add_u64 v[6:7], v[14:15], 0, s[10:11]
	s_mov_b64 s[10:11], 0x3a000
	v_lshl_add_u64 v[8:9], v[14:15], 0, s[10:11]
	s_mov_b64 s[10:11], 0x43000
	v_lshl_add_u64 v[10:11], v[14:15], 0, s[10:11]
	s_mov_b64 s[10:11], 0x4c000
	v_lshl_add_u64 v[12:13], v[14:15], 0, s[10:11]
	s_mov_b64 s[10:11], 0x55000
	v_cmp_eq_u32_e32 vcc, 0, v18
	v_lshl_add_u64 v[14:15], v[14:15], 0, s[10:11]
	s_lshl_b64 s[10:11], s[8:9], 2
	v_lshl_add_u64 v[16:17], v[16:17], 0, s[12:13]
	s_lshl_b64 s[12:13], s[8:9], 11
	v_mov_b32_e32 v25, 0x2f40000
	v_mov_b32_e32 v26, 0x2f45000
	v_mov_b32_e32 v27, 0x2f4b000
	v_mov_b32_e32 v28, 0x2f50000
	v_mov_b32_e32 v29, 0x2f56000
	v_mov_b32_e32 v30, 0x2f5b000
	v_mov_b32_e32 v31, 0x2f61000
	v_mov_b32_e32 v32, 0x2f66000
	s_mov_b32 s9, s2
	s_branch .LBB0_132

.LBB0_148:
	s_cmp_eq_u32 s99, 2
	s_cbranch_scc1 .LBB0_153
	s_cmpk_gt_i32 s2, 0x7ff
	s_cbranch_scc1 .LBB0_153
	v_mbcnt_lo_u32_b32 v1, -1, 0
	v_mbcnt_hi_u32_b32 v1, -1, v1
	v_and_b32_e32 v4, 64, v1
	v_add_u32_e32 v4, 64, v4
	v_xor_b32_e32 v5, 1, v1
	v_cmp_lt_i32_e32 vcc, v5, v4
	s_load_dwordx16 s[36:51], s[0:1], 0x0
	s_add_u32 s9, s82, 0x10000
	v_cndmask_b32_e32 v5, v1, v5, vcc
	v_lshlrev_b32_e32 v54, 2, v5
	v_xor_b32_e32 v5, 2, v1
	v_cmp_lt_i32_e32 vcc, v5, v4
	s_addc_u32 s18, s83, 0
	v_lshlrev_b32_e32 v0, 2, v18
	v_cndmask_b32_e32 v5, v1, v5, vcc
	v_lshlrev_b32_e32 v55, 2, v5
	v_xor_b32_e32 v5, 4, v1
	v_cmp_lt_i32_e32 vcc, v5, v4
	v_mov_b32_e32 v3, 0
	v_lshlrev_b32_e32 v2, 4, v18
	v_cndmask_b32_e32 v5, v1, v5, vcc
	v_lshlrev_b32_e32 v56, 2, v5
	v_xor_b32_e32 v5, 8, v1
	v_cmp_lt_i32_e32 vcc, v5, v4
	s_waitcnt lgkmcnt(0)
	s_mov_b64 s[12:13], s[36:37]
	s_mov_b64 s[20:21], s[44:45]
	v_cndmask_b32_e32 v5, v1, v5, vcc
	v_lshlrev_b32_e32 v57, 2, v5
	v_xor_b32_e32 v5, 16, v1
	v_cmp_lt_i32_e32 vcc, v5, v4
	s_lshl_b32 s6, s96, 7
	s_lshl_b32 s3, s3, 4
	v_cndmask_b32_e32 v5, v1, v5, vcc
	v_lshlrev_b32_e32 v58, 2, v5
	v_xor_b32_e32 v5, 32, v1
	v_cmp_lt_i32_e32 vcc, v5, v4
	v_lshl_add_u64 v[24:25], s[12:13], 0, v[2:3]
	v_lshlrev_b32_e32 v4, 3, v18
	v_cndmask_b32_e32 v1, v1, v5, vcc
	v_mov_b32_e32 v5, v3
	v_lshl_add_u64 v[28:29], s[20:21], 0, v[2:3]
	v_or_b32_e32 v2, 0x100, v0
	v_or_b32_e32 v6, 0x200, v0
	v_or_b32_e32 v8, 0x300, v0
	s_add_i32 s10, s6, s3
	s_mov_b64 s[6:7], 0xc00
	v_lshlrev_b32_e32 v59, 2, v1
	v_lshl_add_u64 v[26:27], s[90:91], 0, v[4:5]
	s_or_b32 s3, s10, 1
	s_lshl_b32 s19, s86, 7
	v_lshl_add_u64 v[30:31], s[82:83], 0, v[4:5]
	v_lshl_add_u64 v[32:33], v[24:25], 0, s[6:7]
	v_lshlrev_b32_e32 v60, 2, v0
	v_lshlrev_b32_e32 v61, 2, v2
	v_lshlrev_b32_e32 v62, 2, v6
	v_lshlrev_b32_e32 v63, 2, v8
	v_mov_b32_e32 v64, 0x358637bd
	s_mov_b32 s20, 0xf800000
	v_mov_b32_e32 v65, 0x260
	s_mov_b32 s21, 0x3000000
	s_mov_b64 s[12:13], 0x2000

.LBB0_151:
	global_load_dwordx4 v[16:19], v[36:37], off offset:-3072
	global_load_dwordx4 v[20:23], v[36:37], off offset:-2048
	global_load_dwordx4 v[66:69], v[36:37], off
	global_load_dwordx4 v[70:73], v[36:37], off offset:-1024
	v_lshl_add_u64 v[74:75], v[34:35], 0, s[14:15]
	v_add_co_u32_e32 v74, vcc, s21, v74
	s_ashr_i32 s17, s16, 31
	s_nop 0
	v_addc_co_u32_e32 v75, vcc, 0, v75, vcc
	s_lshl_b64 s[6:7], s[16:17], 12
	v_lshl_add_u64 v[76:77], v[24:25], 0, s[6:7]
	v_lshl_add_u64 v[36:37], v[36:37], 0, s[12:13]
	s_waitcnt vmcnt(3)
	v_pk_mul_f32 v[78:79], v[18:19], v[18:19]
	v_pk_mul_f32 v[80:81], v[16:17], v[16:17]
	s_waitcnt vmcnt(2)
	v_pk_mul_f32 v[82:83], v[22:23], v[22:23]
	v_pk_mul_f32 v[84:85], v[20:21], v[20:21]
	v_pk_mov_b32 v[90:91], v[80:81], v[78:79] op_sel:[1,0]
	v_mov_b32_e32 v81, v79
	v_pk_mov_b32 v[78:79], v[84:85], v[82:83] op_sel:[1,0]
	v_mov_b32_e32 v85, v83
	s_waitcnt vmcnt(1)
	v_mul_f32_e32 v89, v68, v68
	s_waitcnt vmcnt(0)
	v_mul_f32_e32 v86, v71, v71
	v_mul_f32_e32 v88, v73, v73
	v_pk_add_f32 v[80:81], v[90:91], v[80:81]
	v_pk_add_f32 v[78:79], v[78:79], v[84:85]
	v_mul_f32_e32 v92, v69, v69
	v_mul_f32_e32 v93, v66, v66
	v_mul_f32_e32 v94, v67, v67
	v_pk_fma_f32 v[82:83], v[70:71], v[70:71], v[86:87] op_sel_hi:[1,1,0]
	v_pk_fma_f32 v[86:87], v[72:73], v[72:73], v[88:89] op_sel_hi:[1,1,0]
	v_pk_add_f32 v[80:81], v[80:81], v[80:81] op_sel:[0,1] op_sel_hi:[1,0]
	v_pk_add_f32 v[78:79], v[78:79], v[78:79] op_sel:[0,1] op_sel_hi:[1,0]
	v_mov_b32_e32 v83, v89
	v_mov_b32_e32 v87, v92
	v_mov_b32_e32 v81, v93
	v_mov_b32_e32 v79, v94
	v_pk_add_f32 v[82:83], v[82:83], v[86:87]
	v_pk_add_f32 v[78:79], v[80:81], v[78:79]
	s_nop 0
	v_pk_add_f32 v[78:79], v[78:79], v[82:83]
	s_nop 0
	v_add_f32_e32 v78, v78, v79
	ds_bpermute_b32 v79, v54, v78
	s_waitcnt lgkmcnt(0)
	v_add_f32_e32 v78, v78, v79
	ds_bpermute_b32 v79, v55, v78
	s_waitcnt lgkmcnt(0)
	v_add_f32_e32 v78, v78, v79
	ds_bpermute_b32 v79, v56, v78
	s_waitcnt lgkmcnt(0)
	v_add_f32_e32 v78, v78, v79
	ds_bpermute_b32 v79, v57, v78
	s_waitcnt lgkmcnt(0)
	v_add_f32_e32 v78, v78, v79
	ds_bpermute_b32 v79, v58, v78
	s_waitcnt lgkmcnt(0)
	v_add_f32_e32 v78, v78, v79
	ds_bpermute_b32 v79, v59, v78
	s_waitcnt lgkmcnt(0)
	v_add_f32_e32 v78, v78, v79
	v_fmamk_f32 v78, v78, 0x3a800000, v64
	v_mul_f32_e32 v79, 0x4f800000, v78
	v_cmp_gt_f32_e32 vcc, s20, v78
	s_nop 1
	v_cndmask_b32_e32 v78, v78, v79, vcc
	v_sqrt_f32_e32 v79, v78
	s_nop 0
	v_add_u32_e32 v80, -1, v79
	v_add_u32_e32 v81, 1, v79
	v_fma_f32 v82, -v80, v79, v78
	v_fma_f32 v83, -v81, v79, v78
	v_cmp_ge_f32_e64 s[6:7], 0, v82
	s_nop 1
	v_cndmask_b32_e64 v79, v79, v80, s[6:7]
	v_cmp_lt_f32_e64 s[6:7], 0, v83
	s_nop 1
	v_cndmask_b32_e64 v79, v79, v81, s[6:7]
	v_mul_f32_e32 v80, 0x37800000, v79
	v_cndmask_b32_e32 v79, v79, v80, vcc
	v_cmp_class_f32_e32 vcc, v78, v65
	s_nop 1
	v_cndmask_b32_e32 v78, v79, v78, vcc
	v_div_scale_f32 v79, s[6:7], v78, v78, 1.0
	v_rcp_f32_e32 v81, v79
	v_div_scale_f32 v80, vcc, 1.0, v78, 1.0
	s_lshl_b64 s[6:7], s[16:17], 11
	v_fma_f32 v82, -v79, v81, 1.0
	v_fmac_f32_e32 v81, v82, v81
	v_mul_f32_e32 v82, v80, v81
	v_fma_f32 v83, -v79, v82, v80
	v_fmac_f32_e32 v82, v83, v81
	v_fma_f32 v79, -v79, v82, v80
	v_div_fmas_f32 v79, v79, v81, v82
	v_div_fixup_f32 v78, v79, v78, 1.0
	v_pk_mul_f32 v[16:17], v[16:17], v[78:79] op_sel_hi:[1,0]
	v_pk_mul_f32 v[18:19], v[18:19], v[78:79] op_sel_hi:[1,0]
	v_pk_fma_f32 v[16:17], v[40:41], v[16:17], v[0:1]
	v_pk_mul_f32 v[20:21], v[20:21], v[78:79] op_sel_hi:[1,0]
	v_pk_mul_f32 v[22:23], v[22:23], v[78:79] op_sel_hi:[1,0]
	v_pk_fma_f32 v[18:19], v[38:39], v[18:19], v[2:3]
	v_cvt_pk_bf16_f32 v16, v16, v17
	v_pk_mul_f32 v[70:71], v[70:71], v[78:79] op_sel_hi:[1,0]
	v_cvt_pk_bf16_f32 v17, v18, v19
	v_pk_mul_f32 v[72:73], v[72:73], v[78:79] op_sel_hi:[1,0]
	v_pk_fma_f32 v[22:23], v[42:43], v[22:23], v[6:7]
	v_pk_fma_f32 v[20:21], v[44:45], v[20:21], v[4:5]
	global_store_dwordx2 v[74:75], v[16:17], off
	v_cvt_pk_bf16_f32 v16, v20, v21
	v_cvt_pk_bf16_f32 v17, v22, v23
	v_pk_mul_f32 v[66:67], v[66:67], v[78:79] op_sel_hi:[1,0]
	v_pk_mul_f32 v[68:69], v[68:69], v[78:79] op_sel_hi:[1,0]
	v_pk_fma_f32 v[72:73], v[46:47], v[72:73], v[10:11]
	v_pk_fma_f32 v[70:71], v[48:49], v[70:71], v[8:9]
	global_store_dwordx2 v[74:75], v[16:17], off offset:512
	v_cvt_pk_bf16_f32 v16, v70, v71
	v_cvt_pk_bf16_f32 v17, v72, v73
	v_pk_fma_f32 v[68:69], v[50:51], v[68:69], v[14:15]
	v_pk_fma_f32 v[66:67], v[52:53], v[66:67], v[12:13]
	global_store_dwordx2 v[74:75], v[16:17], off offset:1024
	v_cvt_pk_bf16_f32 v16, v66, v67
	v_cvt_pk_bf16_f32 v17, v68, v69
	global_store_dwordx2 v[74:75], v[16:17], off offset:1536
	global_load_dwordx4 v[16:19], v[76:77], off
	s_nop 0
	global_load_dwordx4 v[20:23], v[76:77], off offset:1024
	global_load_dwordx4 v[66:69], v[76:77], off offset:2048
	global_load_dwordx4 v[70:73], v[76:77], off offset:3072
	v_lshl_add_u64 v[74:75], v[26:27], 0, s[6:7]
	s_add_i32 s16, s16, 2
	s_add_u32 s14, s14, 0x1000
	s_addc_u32 s15, s15, 0
	s_cmpk_lg_u32 s14, 0x8000
	s_waitcnt vmcnt(3)
	v_pk_mul_f32 v[76:77], v[18:19], v[18:19]
	v_pk_mul_f32 v[78:79], v[16:17], v[16:17]
	s_waitcnt vmcnt(2)
	v_pk_mul_f32 v[80:81], v[22:23], v[22:23]
	v_pk_mul_f32 v[82:83], v[20:21], v[20:21]
	v_pk_mov_b32 v[88:89], v[78:79], v[76:77] op_sel:[1,0]
	v_mov_b32_e32 v79, v77
	v_pk_mov_b32 v[76:77], v[82:83], v[80:81] op_sel:[1,0]
	v_mov_b32_e32 v83, v81
	s_waitcnt vmcnt(0)
	v_mul_f32_e32 v87, v70, v70
	v_mul_f32_e32 v84, v67, v67
	v_mul_f32_e32 v86, v69, v69
	v_pk_add_f32 v[78:79], v[88:89], v[78:79]
	v_pk_add_f32 v[76:77], v[76:77], v[82:83]
	v_mul_f32_e32 v90, v72, v72
	v_mul_f32_e32 v91, v73, v73
	v_mul_f32_e32 v92, v71, v71
	v_pk_fma_f32 v[80:81], v[66:67], v[66:67], v[84:85] op_sel_hi:[1,1,0]
	v_pk_fma_f32 v[84:85], v[68:69], v[68:69], v[86:87] op_sel_hi:[1,1,0]
	v_pk_add_f32 v[78:79], v[78:79], v[78:79] op_sel:[0,1] op_sel_hi:[1,0]
	v_pk_add_f32 v[76:77], v[76:77], v[76:77] op_sel:[0,1] op_sel_hi:[1,0]
	v_mov_b32_e32 v81, v90
	v_mov_b32_e32 v85, v91
	v_mov_b32_e32 v79, v87
	v_mov_b32_e32 v77, v92
	v_pk_add_f32 v[80:81], v[80:81], v[84:85]
	v_pk_add_f32 v[76:77], v[78:79], v[76:77]
	s_nop 0
	v_pk_add_f32 v[76:77], v[76:77], v[80:81]
	s_nop 0
	v_add_f32_e32 v76, v76, v77
	ds_bpermute_b32 v77, v54, v76
	s_waitcnt lgkmcnt(0)
	v_add_f32_e32 v76, v76, v77
	ds_bpermute_b32 v77, v55, v76
	s_waitcnt lgkmcnt(0)
	v_add_f32_e32 v76, v76, v77
	ds_bpermute_b32 v77, v56, v76
	s_waitcnt lgkmcnt(0)
	v_add_f32_e32 v76, v76, v77
	ds_bpermute_b32 v77, v57, v76
	s_waitcnt lgkmcnt(0)
	v_add_f32_e32 v76, v76, v77
	ds_bpermute_b32 v77, v58, v76
	s_waitcnt lgkmcnt(0)
	v_add_f32_e32 v76, v76, v77
	ds_bpermute_b32 v77, v59, v76
	s_waitcnt lgkmcnt(0)
	v_add_f32_e32 v76, v76, v77
	v_fmamk_f32 v76, v76, 0x3a800000, v64
	v_mul_f32_e32 v77, 0x4f800000, v76
	v_cmp_gt_f32_e32 vcc, s20, v76
	s_nop 1
	v_cndmask_b32_e32 v76, v76, v77, vcc
	v_sqrt_f32_e32 v77, v76
	s_nop 0
	v_add_u32_e32 v78, -1, v77
	v_add_u32_e32 v79, 1, v77
	v_fma_f32 v80, -v78, v77, v76
	v_fma_f32 v81, -v79, v77, v76
	v_cmp_ge_f32_e64 s[6:7], 0, v80
	s_nop 1
	v_cndmask_b32_e64 v77, v77, v78, s[6:7]
	v_cmp_lt_f32_e64 s[6:7], 0, v81
	s_nop 1
	v_cndmask_b32_e64 v77, v77, v79, s[6:7]
	v_mul_f32_e32 v78, 0x37800000, v77
	v_cndmask_b32_e32 v77, v77, v78, vcc
	v_cmp_class_f32_e32 vcc, v76, v65
	s_nop 1
	v_cndmask_b32_e32 v76, v77, v76, vcc
	v_div_scale_f32 v77, s[6:7], v76, v76, 1.0
	v_rcp_f32_e32 v79, v77
	v_div_scale_f32 v78, vcc, 1.0, v76, 1.0
	v_fma_f32 v80, -v77, v79, 1.0
	v_fmac_f32_e32 v79, v80, v79
	v_mul_f32_e32 v80, v78, v79
	v_fma_f32 v81, -v77, v80, v78
	v_fmac_f32_e32 v80, v81, v79
	v_fma_f32 v77, -v77, v80, v78
	v_div_fmas_f32 v77, v77, v79, v80
	v_div_fixup_f32 v76, v77, v76, 1.0
	v_pk_mul_f32 v[16:17], v[16:17], v[76:77] op_sel_hi:[1,0]
	v_pk_mul_f32 v[18:19], v[18:19], v[76:77] op_sel_hi:[1,0]
	v_pk_fma_f32 v[16:17], v[40:41], v[16:17], v[0:1]
	v_pk_mul_f32 v[20:21], v[20:21], v[76:77] op_sel_hi:[1,0]
	v_pk_mul_f32 v[22:23], v[22:23], v[76:77] op_sel_hi:[1,0]
	v_pk_fma_f32 v[18:19], v[38:39], v[18:19], v[2:3]
	v_cvt_pk_bf16_f32 v16, v16, v17
	v_pk_mul_f32 v[66:67], v[66:67], v[76:77] op_sel_hi:[1,0]
	v_cvt_pk_bf16_f32 v17, v18, v19
	v_pk_mul_f32 v[68:69], v[68:69], v[76:77] op_sel_hi:[1,0]
	v_pk_fma_f32 v[22:23], v[42:43], v[22:23], v[6:7]
	v_pk_fma_f32 v[20:21], v[44:45], v[20:21], v[4:5]
	global_store_dwordx2 v[74:75], v[16:17], off
	v_cvt_pk_bf16_f32 v16, v20, v21
	v_cvt_pk_bf16_f32 v17, v22, v23
	v_pk_mul_f32 v[70:71], v[70:71], v[76:77] op_sel_hi:[1,0]
	v_pk_mul_f32 v[72:73], v[72:73], v[76:77] op_sel_hi:[1,0]
	v_pk_fma_f32 v[68:69], v[46:47], v[68:69], v[10:11]
	v_pk_fma_f32 v[66:67], v[48:49], v[66:67], v[8:9]
	global_store_dwordx2 v[74:75], v[16:17], off offset:512
	v_cvt_pk_bf16_f32 v16, v66, v67
	v_cvt_pk_bf16_f32 v17, v68, v69
	v_pk_fma_f32 v[72:73], v[50:51], v[72:73], v[14:15]
	v_pk_fma_f32 v[70:71], v[52:53], v[70:71], v[12:13]
	global_store_dwordx2 v[74:75], v[16:17], off offset:1024
	v_cvt_pk_bf16_f32 v16, v70, v71
	v_cvt_pk_bf16_f32 v17, v72, v73
	global_store_dwordx2 v[74:75], v[16:17], off offset:1536
	s_cbranch_scc1 .LBB0_151
	s_add_i32 s2, s2, s8
	s_add_i32 s3, s3, s19
	s_add_i32 s10, s10, s19
	s_cmpk_lt_i32 s2, 0x800
	s_cbranch_scc1 .LBB0_150
	s_cmp_eq_u32 s99, 1
	s_cbranch_scc0 .LBB0_153
	s_mov_b32 s99, 2
	v_mov_b32_e32 v0, v236
	s_lshl_b32 s6, s96, 3
	s_nop 0
	v_readfirstlane_b32 s2, v0
	s_ashr_i32 s3, s2, 6
	s_lshl_b32 s8, s86, 3
	s_add_i32 s2, s3, s6
	v_and_b32_e32 v18, 63, v0
	s_cmpk_gt_i32 s2, 0x15ff
	s_cbranch_scc1 .LBB0_153
	s_branch .Lp1_sb
